# GQA main loop: softmax and PV restructured per 16-key group (PV MFMAs of a group overlap the next group's exp/sum/convert), packed in-place score subtraction, O rescale first
# baseline (speedup 1.0000x reference)
; template <int D>
; DI void attn_pass(const bfr* __restrict__ P, int b, int tq_wave, int qcol, int kcol, int vcol, int key0, int nkt, char* smem, f32x16 (&o)[2]) {
;     ...
;   for (int kt = 0; kt < nkt; ++kt) {
;     bfr* sK = sbase + (kt & 1) * 9216;
;     bfr* sV = sK + 64 * 72;
;     { int c = gt, row = c >> 3, kc = c & 7; *(u32x4*)(sK + row * KP + kc * 8) = kreg[0]; }
;     for (int i = 0; i < 1; ++i) {
;       int c = gt, row = c >> 3, kc = c & 7;
;       unsigned wds[4] = {vreg[i].x, vreg[i].y, vreg[i].z, vreg[i].w};
; #pragma unroll
;       for (int e = 0; e < 4; ++e) {
;         sV[(kc * 8 + 2 * e) * 72 + (row ^ (kc << 3))] = (bfr)(wds[e] & 0xffffu);
;         sV[(kc * 8 + 2 * e + 1) * 72 + (row ^ (kc << 3))] = (bfr)(wds[e] >> 16);
;       }
;     }
;     __syncthreads();
;     if (kt + 1 < nkt) {
;       const bfr* Pn = Pb + (size_t)(kt + 1) * 64 * PW;
;       { int c = gt, row = c >> 3, kc = c & 7; kreg[0] = *(const u32x4*)(Pn + (size_t)row * PW + kcol + kc * 8); vreg[0] = *(const u32x4*)(Pn + (size_t)row * PW + vcol + kc * 8); }
;     }
;     f32x16 s[2];
; #pragma unroll
;     for (int t2 = 0; t2 < 2; ++t2) {
; #pragma unroll
;       for (int i = 0; i < 16; ++i) s[t2][i] = 0.f;
; #pragma unroll
;       for (int ks = 0; ks < KS; ++ks) {
;         bf16x8 a = *(const bf16x8*)(sK + (t2 * 32 + r) * KP + ks * 16 + h * 8);
;         s[t2] = MFMA32(a, qf[ks], s[t2]);
;       }
;     }
;     float mx = s[0][0];
; #pragma unroll
;     for (int i = 0; i < 16; ++i) { mx = fmaxf(mx, s[0][i]); mx = fmaxf(mx, s[1][i]); }
;     mx = fmaxf(mx, __shfl_xor(mx, 32));
;     float mnew = fmaxf(mrun, mx);
;     float alpha = __builtin_amdgcn_exp2f(mrun - mnew);
;     mrun = mnew;
;     float ps = 0.f;
; #pragma unroll
;     for (int i = 0; i < 16; ++i) {
;       s[0][i] = __builtin_amdgcn_exp2f(s[0][i] - mnew); ps += s[0][i];
;       s[1][i] = __builtin_amdgcn_exp2f(s[1][i] - mnew); ps += s[1][i];
;     }
;     lsum = lsum * alpha + ps;
; #pragma unroll
;     for (int i = 0; i < 16; ++i) { accO[0][i] *= alpha; accO[1][i] *= alpha; }
; #pragma unroll
;     for (int t2 = 0; t2 < 2; ++t2)
; #pragma unroll
;       for (int j = 0; j < 2; ++j) {
;         unsigned pk[4];
; #pragma unroll
;         for (int e = 0; e < 4; ++e) pk[e] = pack2(s[t2][8 * j + 2 * e], s[t2][8 * j + 2 * e + 1]);
;         u32x4 pku = {pk[0], pk[1], pk[2], pk[3]};
.LBB0_412:
	s_bitcmp1_b32 s8, 0
	s_cselect_b32 s9, 0x4800, 0
	s_add_i32 s9, s9, 0
	v_add3_u32 v32, s9, v115, v90
	v_add_u32_e32 v121, s9, v114
	v_mov_b32_e32 v120, v113
	s_waitcnt vmcnt(1)
	ds_write_b128 v32, v[84:87]
	v_add3_u32 v32, s9, v117, v118
	v_add3_u32 v33, s9, v118, v117
	v_add_u32_e32 v113, v121, v152
	s_waitcnt vmcnt(0)
	ds_write_b16 v32, v80 offset:9216
	ds_write_b16_d16_hi v33, v80 offset:9360
	ds_write_b16 v32, v81 offset:9504
	ds_write_b16_d16_hi v33, v81 offset:9648
	ds_write_b16 v32, v82 offset:9792
	ds_write_b16_d16_hi v33, v82 offset:9936
	ds_write_b16 v32, v83 offset:10080
	ds_write_b16_d16_hi v33, v83 offset:10224
	s_waitcnt lgkmcnt(0)
	s_barrier
	global_load_dwordx4 v[84:87], v[92:93], off
	global_load_dwordx4 v[80:83], v[94:95], off
	ds_read_b128 v[126:129], v113
	ds_read_b128 v[130:133], v113 offset:32
	ds_read_b128 v[134:137], v113 offset:64
	ds_read_b128 v[138:141], v113 offset:96
	ds_read_b128 v[142:145], v113 offset:4608
	ds_read_b128 v[146:149], v113 offset:4640
	ds_read_b128 v[156:159], v113 offset:4672
	ds_read_b128 v[164:167], v113 offset:4704
	v_mov_b32_e32 v96, v119
	s_waitcnt lgkmcnt(7)
	v_mfma_f32_32x32x16_bf16 v[32:47], v[126:129], v[76:79], 0
	s_add_i32 s8, s8, 1
	s_waitcnt lgkmcnt(6)
	v_mfma_f32_32x32x16_bf16 v[32:47], v[130:133], v[72:75], v[32:47]
	v_lshl_add_u64 v[92:93], v[92:93], 0, s[10:11]
	s_waitcnt lgkmcnt(5)
	v_mfma_f32_32x32x16_bf16 v[32:47], v[134:137], v[68:71], v[32:47]
	v_lshl_add_u64 v[94:95], v[94:95], 0, s[10:11]
	s_waitcnt lgkmcnt(4)
	v_mfma_f32_32x32x16_bf16 v[32:47], v[138:141], v[64:67], v[32:47]
	s_cmp_lg_u32 s8, 35
	s_waitcnt lgkmcnt(3)
	v_mfma_f32_32x32x16_bf16 v[48:63], v[142:145], v[76:79], 0
	s_waitcnt lgkmcnt(2)
	v_mfma_f32_32x32x16_bf16 v[48:63], v[146:149], v[72:75], v[48:63]
	s_waitcnt lgkmcnt(1)
	v_mfma_f32_32x32x16_bf16 v[48:63], v[156:159], v[68:71], v[48:63]
	s_waitcnt lgkmcnt(0)
	v_mfma_f32_32x32x16_bf16 v[48:63], v[164:167], v[64:67], v[48:63]
	v_add_u32_e32 v154, s9, v116
	v_lshl_add_u32 v168, v112, 1, v121
	v_lshl_add_u32 v169, v111, 1, v121
	v_lshl_add_u32 v170, v110, 1, v154
	v_lshl_add_u32 v171, v109, 1, v154
	v_lshl_add_u32 v172, v108, 1, v121
	v_lshl_add_u32 v173, v107, 1, v121
	v_lshl_add_u32 v174, v106, 1, v154
	v_lshl_add_u32 v175, v105, 1, v154
	v_lshl_add_u32 v176, v104, 1, v121
	v_lshl_add_u32 v177, v103, 1, v154
	v_lshl_add_u32 v178, v102, 1, v154
	v_lshl_add_u32 v179, v100, 1, v121
	v_lshl_add_u32 v180, v101, 1, v121
	v_lshl_add_u32 v181, v99, 1, v154
	v_lshl_add_u32 v160, v98, 1, v154
	v_max_f32_e32 v119, v32, v32
	v_max_f32_e32 v113, v48, v48
	v_max_f32_e32 v113, v119, v113
	v_max3_f32 v113, v113, v33, v49
	v_max3_f32 v113, v113, v34, v50
	v_max3_f32 v113, v113, v35, v51
	v_max3_f32 v113, v113, v36, v52
	v_max3_f32 v113, v113, v37, v53
	v_max3_f32 v113, v113, v38, v54
	v_max3_f32 v113, v113, v39, v55
	v_max3_f32 v113, v113, v40, v56
	v_max3_f32 v113, v113, v41, v57
	v_max3_f32 v113, v113, v42, v58
	v_max3_f32 v113, v113, v43, v59
	v_max3_f32 v113, v113, v44, v60
	v_max3_f32 v113, v113, v45, v61
	v_max3_f32 v113, v113, v46, v62
	v_max3_f32 v113, v113, v47, v63
	ds_bpermute_b32 v119, v91, v113
	s_waitcnt lgkmcnt(0)
	ds_read_b64 v[126:127], v168 offset:9216
	ds_read_b64 v[128:129], v169 offset:9216
	ds_read_b64 v[130:131], v170 offset:9216
	ds_read_b64 v[132:133], v171 offset:9216
	ds_read_b64 v[134:135], v172 offset:9216
	ds_read_b64 v[136:137], v173 offset:9216
	ds_read_b64 v[138:139], v174 offset:9216
	ds_read_b64 v[140:141], v175 offset:9216
	v_max3_f32 v119, v96, v113, v119
	v_sub_f32_e32 v96, v96, v119
	v_exp_f32_e32 v96, v96
	v_pk_add_f32 v[32:33], v[32:33], v[118:119] op_sel:[0,1] op_sel_hi:[1,1] neg_lo:[0,1] neg_hi:[0,1]
	v_pk_add_f32 v[34:35], v[34:35], v[118:119] op_sel:[0,1] op_sel_hi:[1,1] neg_lo:[0,1] neg_hi:[0,1]
	v_pk_add_f32 v[36:37], v[36:37], v[118:119] op_sel:[0,1] op_sel_hi:[1,1] neg_lo:[0,1] neg_hi:[0,1]
	v_pk_add_f32 v[38:39], v[38:39], v[118:119] op_sel:[0,1] op_sel_hi:[1,1] neg_lo:[0,1] neg_hi:[0,1]
	v_exp_f32_e32 v32, v32
	v_pk_mul_f32 v[30:31], v[30:31], v[96:97] op_sel_hi:[1,0]
	v_exp_f32_e32 v33, v33
	v_pk_mul_f32 v[28:29], v[28:29], v[96:97] op_sel_hi:[1,0]
	v_exp_f32_e32 v34, v34
	v_pk_mul_f32 v[26:27], v[26:27], v[96:97] op_sel_hi:[1,0]
	v_exp_f32_e32 v35, v35
	v_pk_mul_f32 v[24:25], v[24:25], v[96:97] op_sel_hi:[1,0]
	v_exp_f32_e32 v36, v36
	v_pk_mul_f32 v[22:23], v[22:23], v[96:97] op_sel_hi:[1,0]
	v_exp_f32_e32 v37, v37
	v_pk_mul_f32 v[20:21], v[20:21], v[96:97] op_sel_hi:[1,0]
	v_exp_f32_e32 v38, v38
	v_pk_mul_f32 v[18:19], v[18:19], v[96:97] op_sel_hi:[1,0]
	v_exp_f32_e32 v39, v39
	v_pk_mul_f32 v[16:17], v[16:17], v[96:97] op_sel_hi:[1,0]
	s_waitcnt lgkmcnt(4)
	ds_read_b64 v[142:143], v168 offset:9280
	ds_read_b64 v[144:145], v176 offset:9216
	ds_read_b64 v[146:147], v177 offset:9216
	ds_read_b64 v[148:149], v178 offset:9216
	ds_read_b64 v[156:157], v179 offset:9216
	ds_read_b64 v[158:159], v180 offset:9216
	ds_read_b64 v[164:165], v181 offset:9216
	ds_read_b64 v[166:167], v160 offset:9216
	v_pk_mul_f32 v[14:15], v[14:15], v[96:97] op_sel_hi:[1,0]
	v_pk_mul_f32 v[12:13], v[12:13], v[96:97] op_sel_hi:[1,0]
	v_pk_mul_f32 v[10:11], v[10:11], v[96:97] op_sel_hi:[1,0]
	v_pk_mul_f32 v[8:9], v[8:9], v[96:97] op_sel_hi:[1,0]
	v_pk_mul_f32 v[6:7], v[6:7], v[96:97] op_sel_hi:[1,0]
	v_pk_mul_f32 v[4:5], v[4:5], v[96:97] op_sel_hi:[1,0]
	v_pk_mul_f32 v[2:3], v[2:3], v[96:97] op_sel_hi:[1,0]
	v_pk_mul_f32 v[0:1], v[0:1], v[96:97] op_sel_hi:[1,0]
	v_add_f32_e32 v113, v32, v33
	v_add_f32_e32 v113, v34, v113
	v_add_f32_e32 v113, v35, v113
	v_add_f32_e32 v113, v36, v113
	v_add_f32_e32 v113, v37, v113
	v_add_f32_e32 v113, v38, v113
	v_add_f32_e32 v113, v39, v113
	v_cvt_pk_bf16_f32 v32, v32, v33
	v_cvt_pk_bf16_f32 v33, v34, v35
	v_cvt_pk_bf16_f32 v34, v36, v37
	v_cvt_pk_bf16_f32 v35, v38, v39
	s_nop 1
	s_waitcnt lgkmcnt(8)
; template <int D>
; DI void attn_pass(const bfr* __restrict__ P, int b, int tq_wave, int qcol, int kcol, int vcol, int key0, int nkt, char* smem, f32x16 (&o)[2]) {
;     ...
;   for (int kt = 0; kt < nkt; ++kt) {
;     bfr* sK = sbase + (kt & 1) * 9216;
;     bfr* sV = sK + 64 * 72;
;     { int c = gt, row = c >> 3, kc = c & 7; *(u32x4*)(sK + row * KP + kc * 8) = kreg[0]; }
;     for (int i = 0; i < 1; ++i) {
;       int c = gt, row = c >> 3, kc = c & 7;
;       unsigned wds[4] = {vreg[i].x, vreg[i].y, vreg[i].z, vreg[i].w};
; #pragma unroll
;       for (int e = 0; e < 4; ++e) {
;         sV[(kc * 8 + 2 * e) * 72 + (row ^ (kc << 3))] = (bfr)(wds[e] & 0xffffu);
;         sV[(kc * 8 + 2 * e + 1) * 72 + (row ^ (kc << 3))] = (bfr)(wds[e] >> 16);
;       }
;     }
;     __syncthreads();
;     if (kt + 1 < nkt) {
;       const bfr* Pn = Pb + (size_t)(kt + 1) * 64 * PW;
;       { int c = gt, row = c >> 3, kc = c & 7; kreg[0] = *(const u32x4*)(Pn + (size_t)row * PW + kcol + kc * 8); vreg[0] = *(const u32x4*)(Pn + (size_t)row * PW + vcol + kc * 8); }
;     }
;     f32x16 s[2];
; #pragma unroll
;     for (int t2 = 0; t2 < 2; ++t2) {
; #pragma unroll
;     ...
;     float ps = 0.f;
; #pragma unroll
;     for (int i = 0; i < 16; ++i) {
;       s[0][i] = __builtin_amdgcn_exp2f(s[0][i] - mnew); ps += s[0][i];
;       s[1][i] = __builtin_amdgcn_exp2f(s[1][i] - mnew); ps += s[1][i];
;     }
;     lsum = lsum * alpha + ps;
; #pragma unroll
;     for (int i = 0; i < 16; ++i) { accO[0][i] *= alpha; accO[1][i] *= alpha; }
; #pragma unroll
;     for (int t2 = 0; t2 < 2; ++t2)
; #pragma unroll
;       for (int j = 0; j < 2; ++j) {
;         unsigned pk[4];
; #pragma unroll
;         for (int e = 0; e < 4; ++e) pk[e] = pack2(s[t2][8 * j + 2 * e], s[t2][8 * j + 2 * e + 1]);
;         u32x4 pku = {pk[0], pk[1], pk[2], pk[3]};
;         bf16x8 pf = __builtin_bit_cast(bf16x8, pku);
; #pragma unroll
;         for (int dt = 0; dt < 2; ++dt) {
;           const int vsw = (((dt * 32 + r) >> 3) & 7) << 3;
;           const bfr* vrow = sV + (dt * 32 + r) * 72;
;           s16x4 lo = *(const s16x4*)(vrow + ((t2 * 32 + 16 * j + 4 * h) ^ vsw));
;           s16x4 hi = *(const s16x4*)(vrow + ((t2 * 32 + 16 * j + 4 * h + 8) ^ vsw));
;           bf16x8 vf = __builtin_shufflevector(lo, hi, 0, 1, 2, 3, 4, 5, 6, 7);
;           accO[dt] = MFMA32(vf, pf, accO[dt]);
;         }
;       }
	v_mfma_f32_32x32x16_bf16 v[16:31], v[126:129], v[32:35], v[16:31]
	v_mfma_f32_32x32x16_bf16 v[0:15], v[130:133], v[32:35], v[0:15]
	v_pk_add_f32 v[40:41], v[40:41], v[118:119] op_sel:[0,1] op_sel_hi:[1,1] neg_lo:[0,1] neg_hi:[0,1]
	v_pk_add_f32 v[42:43], v[42:43], v[118:119] op_sel:[0,1] op_sel_hi:[1,1] neg_lo:[0,1] neg_hi:[0,1]
	v_pk_add_f32 v[44:45], v[44:45], v[118:119] op_sel:[0,1] op_sel_hi:[1,1] neg_lo:[0,1] neg_hi:[0,1]
	v_pk_add_f32 v[46:47], v[46:47], v[118:119] op_sel:[0,1] op_sel_hi:[1,1] neg_lo:[0,1] neg_hi:[0,1]
	v_exp_f32_e32 v40, v40
	v_exp_f32_e32 v41, v41
	v_exp_f32_e32 v42, v42
	v_exp_f32_e32 v43, v43
	v_exp_f32_e32 v44, v44
	v_exp_f32_e32 v45, v45
	v_exp_f32_e32 v46, v46
	v_exp_f32_e32 v47, v47
	v_add_f32_e32 v113, v40, v113
	v_add_f32_e32 v113, v41, v113
	v_add_f32_e32 v113, v42, v113
	v_add_f32_e32 v113, v43, v113
	v_add_f32_e32 v113, v44, v113
	v_add_f32_e32 v113, v45, v113
	v_add_f32_e32 v113, v46, v113
	v_add_f32_e32 v113, v47, v113
	v_cvt_pk_bf16_f32 v32, v40, v41
	v_cvt_pk_bf16_f32 v33, v42, v43
	v_cvt_pk_bf16_f32 v34, v44, v45
	v_cvt_pk_bf16_f32 v35, v46, v47
	s_nop 1
	v_mfma_f32_32x32x16_bf16 v[16:31], v[134:137], v[32:35], v[16:31]
	v_mfma_f32_32x32x16_bf16 v[0:15], v[138:141], v[32:35], v[0:15]
	v_pk_add_f32 v[48:49], v[48:49], v[118:119] op_sel:[0,1] op_sel_hi:[1,1] neg_lo:[0,1] neg_hi:[0,1]
	v_pk_add_f32 v[50:51], v[50:51], v[118:119] op_sel:[0,1] op_sel_hi:[1,1] neg_lo:[0,1] neg_hi:[0,1]
	v_pk_add_f32 v[52:53], v[52:53], v[118:119] op_sel:[0,1] op_sel_hi:[1,1] neg_lo:[0,1] neg_hi:[0,1]
	v_pk_add_f32 v[54:55], v[54:55], v[118:119] op_sel:[0,1] op_sel_hi:[1,1] neg_lo:[0,1] neg_hi:[0,1]
	v_exp_f32_e32 v48, v48
	v_exp_f32_e32 v49, v49
	v_exp_f32_e32 v50, v50
	v_exp_f32_e32 v51, v51
	v_exp_f32_e32 v52, v52
	v_exp_f32_e32 v53, v53
	v_exp_f32_e32 v54, v54
	v_exp_f32_e32 v55, v55
	v_add_f32_e32 v113, v48, v113
	v_add_f32_e32 v113, v49, v113
	v_add_f32_e32 v113, v50, v113
	v_add_f32_e32 v113, v51, v113
	v_add_f32_e32 v113, v52, v113
	v_add_f32_e32 v113, v53, v113
	v_add_f32_e32 v113, v54, v113
	v_add_f32_e32 v113, v55, v113
	v_cvt_pk_bf16_f32 v32, v48, v49
	v_cvt_pk_bf16_f32 v33, v50, v51
	v_cvt_pk_bf16_f32 v34, v52, v53
	v_cvt_pk_bf16_f32 v35, v54, v55
	s_nop 1
	s_waitcnt lgkmcnt(4)
	v_mfma_f32_32x32x16_bf16 v[16:31], v[142:145], v[32:35], v[16:31]
	v_mfma_f32_32x32x16_bf16 v[0:15], v[146:149], v[32:35], v[0:15]
	v_pk_add_f32 v[56:57], v[56:57], v[118:119] op_sel:[0,1] op_sel_hi:[1,1] neg_lo:[0,1] neg_hi:[0,1]
	v_pk_add_f32 v[58:59], v[58:59], v[118:119] op_sel:[0,1] op_sel_hi:[1,1] neg_lo:[0,1] neg_hi:[0,1]
	v_pk_add_f32 v[60:61], v[60:61], v[118:119] op_sel:[0,1] op_sel_hi:[1,1] neg_lo:[0,1] neg_hi:[0,1]
	v_pk_add_f32 v[62:63], v[62:63], v[118:119] op_sel:[0,1] op_sel_hi:[1,1] neg_lo:[0,1] neg_hi:[0,1]
	v_exp_f32_e32 v56, v56
	v_exp_f32_e32 v57, v57
	v_exp_f32_e32 v58, v58
	v_exp_f32_e32 v59, v59
	v_exp_f32_e32 v60, v60
	v_exp_f32_e32 v61, v61
	v_exp_f32_e32 v62, v62
	v_exp_f32_e32 v63, v63
	v_add_f32_e32 v113, v56, v113
	v_add_f32_e32 v113, v57, v113
	v_add_f32_e32 v113, v58, v113
	v_add_f32_e32 v113, v59, v113
	v_add_f32_e32 v113, v60, v113
	v_add_f32_e32 v113, v61, v113
	v_add_f32_e32 v113, v62, v113
	v_add_f32_e32 v113, v63, v113
	v_cvt_pk_bf16_f32 v32, v56, v57
	v_cvt_pk_bf16_f32 v33, v58, v59
	v_cvt_pk_bf16_f32 v34, v60, v61
	v_cvt_pk_bf16_f32 v35, v62, v63
	s_nop 1
	s_waitcnt lgkmcnt(0)
	v_mfma_f32_32x32x16_bf16 v[16:31], v[156:159], v[32:35], v[16:31]
	v_mfma_f32_32x32x16_bf16 v[0:15], v[164:167], v[32:35], v[0:15]
	v_fmac_f32_e32 v113, v120, v96
	s_cbranch_scc1 .LBB0_412
	v_add3_u32 v32, 0, v115, v90
	s_waitcnt vmcnt(1)
	ds_write_b128 v32, v[84:87] offset:18432
	v_add3_u32 v32, 0, v117, v118
	v_add3_u32 v33, 0, v118, v117
	s_waitcnt vmcnt(0)
	ds_write_b16 v32, v80 offset:27648
	ds_write_b16_d16_hi v33, v80 offset:27792
	ds_write_b16 v32, v81 offset:27936
	ds_write_b16_d16_hi v33, v81 offset:28080
	ds_write_b16 v32, v82 offset:28224
	ds_write_b16_d16_hi v33, v82 offset:28368
	ds_write_b16 v32, v83 offset:28512
	ds_write_b16_d16_hi v33, v83 offset:28656
	v_add_u32_e32 v80, 0, v114
	v_add_u32_e32 v81, v80, v152
	s_waitcnt lgkmcnt(0)
	s_barrier
	ds_read_b128 v[32:35], v81 offset:18432
	ds_read_b128 v[48:51], v81 offset:18464
	s_waitcnt lgkmcnt(1)
	v_mfma_f32_32x32x16_bf16 v[32:47], v[32:35], v[76:79], 0
	v_lshlrev_b32_e32 v152, 1, v88
	s_waitcnt lgkmcnt(0)
	v_mfma_f32_32x32x16_bf16 v[32:47], v[48:51], v[72:75], v[32:47]
	ds_read_b128 v[48:51], v81 offset:18496
	s_waitcnt lgkmcnt(0)
	v_mfma_f32_32x32x16_bf16 v[32:47], v[48:51], v[68:71], v[32:47]
	ds_read_b128 v[48:51], v81 offset:18528
	s_waitcnt lgkmcnt(0)
	v_mfma_f32_32x32x16_bf16 v[32:47], v[48:51], v[64:67], v[32:47]
	ds_read_b128 v[48:51], v81 offset:23040
	s_waitcnt lgkmcnt(0)
	v_mfma_f32_32x32x16_bf16 v[48:63], v[48:51], v[76:79], 0
	ds_read_b128 v[76:79], v81 offset:23072
	s_waitcnt lgkmcnt(0)
	v_mfma_f32_32x32x16_bf16 v[48:63], v[76:79], v[72:75], v[48:63]
	ds_read_b128 v[72:75], v81 offset:23104
	s_waitcnt lgkmcnt(0)
	v_mfma_f32_32x32x16_bf16 v[48:63], v[72:75], v[68:71], v[48:63]
	ds_read_b128 v[68:71], v81 offset:23136
	s_waitcnt lgkmcnt(0)
	v_mfma_f32_32x32x16_bf16 v[48:63], v[68:71], v[64:67], v[48:63]
	v_max_f32_e32 v65, v32, v32
	v_lshl_add_u32 v66, v112, 1, v80
	v_add_u32_e32 v67, 0x1200, v80
	s_nop 8
	v_max_f32_e32 v64, v48, v48
	v_max_f32_e32 v64, v65, v64
	v_max3_f32 v64, v64, v33, v49
	v_max3_f32 v64, v64, v34, v50
	v_max3_f32 v64, v64, v35, v51
	v_max3_f32 v64, v64, v36, v52
	v_max3_f32 v64, v64, v37, v53
	v_max3_f32 v64, v64, v38, v54
	v_max3_f32 v64, v64, v39, v55
	v_max3_f32 v64, v64, v40, v56
	v_max3_f32 v64, v64, v41, v57
	v_max3_f32 v64, v64, v42, v58
	v_max3_f32 v64, v64, v43, v59
	v_max3_f32 v64, v64, v44, v60
	v_max3_f32 v64, v64, v45, v61
	v_max3_f32 v64, v64, v46, v62
	v_max3_f32 v64, v64, v47, v63
	ds_bpermute_b32 v65, v91, v64
	s_waitcnt lgkmcnt(0)
; #define MFMA32(a, b, c) __builtin_amdgcn_mfma_f32_32x32x16_bf16((a), (b), (c), 0, 0, 0)
; DI unsigned pack2(float a, float b) { unsigned r; asm volatile("v_cvt_pk_bf16_f32 %0, %1, %2" : "=v"(r) : "v"(a), "v"(b)); return r; }
; template <int D>
; DI void attn_pass(const bfr* __restrict__ P, int b, int tq_wave, int qcol, int kcol, int vcol, int key0, int nkt, char* smem, f32x16 (&o)[2]) {
;     ...
;     float mx = s[0][0];
; #pragma unroll
;     for (int i = 0; i < 16; ++i) { mx = fmaxf(mx, s[0][i]); mx = fmaxf(mx, s[1][i]); }
;     mx = fmaxf(mx, __shfl_xor(mx, 32));
;     float mnew = fmaxf(mrun, mx);
;     float alpha = __builtin_amdgcn_exp2f(mrun - mnew);
;     mrun = mnew;
;     float ps = 0.f;
; #pragma unroll
;     for (int i = 0; i < 16; ++i) {
;       s[0][i] = __builtin_amdgcn_exp2f(s[0][i] - mnew); ps += s[0][i];
;       s[1][i] = __builtin_amdgcn_exp2f(s[1][i] - mnew); ps += s[1][i];
;     }
;     lsum = lsum * alpha + ps;
; #pragma unroll
;     for (int i = 0; i < 16; ++i) { accO[0][i] *= alpha; accO[1][i] *= alpha; }
; #pragma unroll
;     for (int t2 = 0; t2 < 2; ++t2)
; #pragma unroll
;       for (int j = 0; j < 2; ++j) {
;         unsigned pk[4];
; #pragma unroll
;         for (int e = 0; e < 4; ++e) pk[e] = pack2(s[t2][8 * j + 2 * e], s[t2][8 * j + 2 * e + 1]);
;         u32x4 pku = {pk[0], pk[1], pk[2], pk[3]};
;         bf16x8 pf = __builtin_bit_cast(bf16x8, pku);
; #pragma unroll
;         for (int dt = 0; dt < 2; ++dt) {
;           const int vsw = (((dt * 32 + r) >> 3) & 7) << 3;
;           const bfr* vrow = sV + (dt * 32 + r) * 72;
;           s16x4 lo = *(const s16x4*)(vrow + ((t2 * 32 + 16 * j + 4 * h) ^ vsw));
;           s16x4 hi = *(const s16x4*)(vrow + ((t2 * 32 + 16 * j + 4 * h + 8) ^ vsw));
;           bf16x8 vf = __builtin_shufflevector(lo, hi, 0, 1, 2, 3, 4, 5, 6, 7);
;           accO[dt] = MFMA32(vf, pf, accO[dt]);
;         }
;       }
	v_max3_f32 v65, v119, v64, v65
	v_sub_f32_e32 v64, v119, v65
	v_sub_f32_e32 v32, v32, v65
	v_exp_f32_e32 v64, v64
	v_exp_f32_e32 v32, v32
	v_sub_f32_e32 v48, v48, v65
	v_exp_f32_e32 v48, v48
	v_sub_f32_e32 v33, v33, v65
	v_exp_f32_e32 v33, v33
	v_sub_f32_e32 v49, v49, v65
	v_exp_f32_e32 v49, v49
	v_sub_f32_e32 v34, v34, v65
	v_exp_f32_e32 v34, v34
	v_sub_f32_e32 v50, v50, v65
	v_sub_f32_e32 v35, v35, v65
	v_sub_f32_e32 v51, v51, v65
	v_sub_f32_e32 v36, v36, v65
	v_sub_f32_e32 v52, v52, v65
	v_sub_f32_e32 v37, v37, v65
	v_sub_f32_e32 v53, v53, v65
	v_sub_f32_e32 v38, v38, v65
	v_sub_f32_e32 v54, v54, v65
	v_sub_f32_e32 v39, v39, v65
	v_sub_f32_e32 v55, v55, v65
	v_sub_f32_e32 v40, v40, v65
	v_sub_f32_e32 v56, v56, v65
	v_sub_f32_e32 v41, v41, v65
	v_sub_f32_e32 v57, v57, v65
	v_sub_f32_e32 v42, v42, v65
	v_sub_f32_e32 v58, v58, v65
	v_sub_f32_e32 v43, v43, v65
	v_sub_f32_e32 v59, v59, v65
	v_sub_f32_e32 v44, v44, v65
	v_sub_f32_e32 v60, v60, v65
	v_sub_f32_e32 v45, v45, v65
	v_sub_f32_e32 v61, v61, v65
	v_sub_f32_e32 v46, v46, v65
	v_sub_f32_e32 v62, v62, v65
	v_sub_f32_e32 v47, v47, v65
	v_sub_f32_e32 v63, v63, v65
	v_pk_mul_f32 v[30:31], v[30:31], v[64:65] op_sel_hi:[1,0]
	v_pk_mul_f32 v[28:29], v[28:29], v[64:65] op_sel_hi:[1,0]
	v_pk_mul_f32 v[26:27], v[26:27], v[64:65] op_sel_hi:[1,0]
	v_pk_mul_f32 v[24:25], v[24:25], v[64:65] op_sel_hi:[1,0]
	v_pk_mul_f32 v[22:23], v[22:23], v[64:65] op_sel_hi:[1,0]
	v_pk_mul_f32 v[20:21], v[20:21], v[64:65] op_sel_hi:[1,0]
	v_pk_mul_f32 v[18:19], v[18:19], v[64:65] op_sel_hi:[1,0]
	v_pk_mul_f32 v[16:17], v[16:17], v[64:65] op_sel_hi:[1,0]
	v_pk_mul_f32 v[14:15], v[14:15], v[64:65] op_sel_hi:[1,0]
	v_pk_mul_f32 v[12:13], v[12:13], v[64:65] op_sel_hi:[1,0]
	v_pk_mul_f32 v[10:11], v[10:11], v[64:65] op_sel_hi:[1,0]
	v_pk_mul_f32 v[8:9], v[8:9], v[64:65] op_sel_hi:[1,0]
	v_pk_mul_f32 v[6:7], v[6:7], v[64:65] op_sel_hi:[1,0]
	v_pk_mul_f32 v[4:5], v[4:5], v[64:65] op_sel_hi:[1,0]
	v_pk_mul_f32 v[2:3], v[2:3], v[64:65] op_sel_hi:[1,0]
	v_pk_mul_f32 v[0:1], v[0:1], v[64:65] op_sel_hi:[1,0]
	v_add_f32_e32 v65, 0, v32
	v_exp_f32_e32 v50, v50
	v_add_f32_e32 v65, v48, v65
	v_exp_f32_e32 v35, v35
	v_add_f32_e32 v65, v33, v65
	v_exp_f32_e32 v51, v51
	v_add_f32_e32 v65, v49, v65
	v_exp_f32_e32 v36, v36
	v_add_f32_e32 v65, v34, v65
	v_exp_f32_e32 v52, v52
	v_add_f32_e32 v65, v50, v65
	v_exp_f32_e32 v37, v37
	v_add_f32_e32 v65, v35, v65
	v_exp_f32_e32 v53, v53
	v_add_f32_e32 v65, v51, v65
	v_exp_f32_e32 v38, v38
	v_add_f32_e32 v65, v36, v65
	v_exp_f32_e32 v54, v54
	v_add_f32_e32 v65, v52, v65
	v_exp_f32_e32 v39, v39
	v_add_f32_e32 v65, v37, v65
	v_add_f32_e32 v65, v53, v65
	v_add_f32_e32 v65, v38, v65
	v_add_f32_e32 v65, v54, v65
	v_cvt_pk_bf16_f32 v32, v32, v33
	v_cvt_pk_bf16_f32 v33, v34, v35
	v_cvt_pk_bf16_f32 v34, v36, v37
	v_cvt_pk_bf16_f32 v35, v38, v39
	v_lshl_add_u32 v38, v111, 1, v80
	v_add_f32_e32 v65, v39, v65
	ds_read_b64 v[36:37], v66 offset:27648
	ds_read_b64 v[38:39], v38 offset:27648
	s_waitcnt lgkmcnt(0)
	v_mfma_f32_32x32x16_bf16 v[16:31], v[36:39], v[32:35], v[16:31]
	v_lshl_add_u32 v36, v110, 1, v67
	v_lshl_add_u32 v38, v109, 1, v67
	ds_read_b64 v[36:37], v36 offset:27648
	ds_read_b64 v[38:39], v38 offset:27648
	v_exp_f32_e32 v40, v40
	v_exp_f32_e32 v41, v41
	v_exp_f32_e32 v42, v42
	s_waitcnt lgkmcnt(0)
	v_mfma_f32_32x32x16_bf16 v[0:15], v[36:39], v[32:35], v[0:15]
	v_lshl_add_u32 v36, v108, 1, v80
	v_lshl_add_u32 v38, v107, 1, v80
	v_exp_f32_e32 v43, v43
	v_exp_f32_e32 v44, v44
	v_exp_f32_e32 v45, v45
	v_exp_f32_e32 v46, v46
	v_exp_f32_e32 v47, v47
	v_cvt_pk_bf16_f32 v32, v40, v41
	v_cvt_pk_bf16_f32 v33, v42, v43
	v_cvt_pk_bf16_f32 v34, v44, v45
	v_cvt_pk_bf16_f32 v35, v46, v47
	ds_read_b64 v[36:37], v36 offset:27648
	ds_read_b64 v[38:39], v38 offset:27648
	s_waitcnt lgkmcnt(0)
	v_mfma_f32_32x32x16_bf16 v[16:31], v[36:39], v[32:35], v[16:31]
	v_lshl_add_u32 v36, v106, 1, v67
	v_lshl_add_u32 v38, v105, 1, v67
	ds_read_b64 v[36:37], v36 offset:27648
	ds_read_b64 v[38:39], v38 offset:27648
	v_exp_f32_e32 v55, v55
	v_exp_f32_e32 v56, v56
	v_exp_f32_e32 v57, v57
	s_waitcnt lgkmcnt(0)
	v_mfma_f32_32x32x16_bf16 v[0:15], v[36:39], v[32:35], v[0:15]
	v_lshl_add_u32 v38, v104, 1, v80
	v_cvt_pk_bf16_f32 v32, v48, v49
	v_cvt_pk_bf16_f32 v33, v50, v51
	v_cvt_pk_bf16_f32 v34, v52, v53
	v_cvt_pk_bf16_f32 v35, v54, v55
	ds_read_b64 v[36:37], v66 offset:27712
	ds_read_b64 v[38:39], v38 offset:27648
	s_waitcnt lgkmcnt(0)
; DI unsigned pack2(float a, float b) { unsigned r; asm volatile("v_cvt_pk_bf16_f32 %0, %1, %2" : "=v"(r) : "v"(a), "v"(b)); return r; }
; template <int D>
; DI void attn_pass(const bfr* __restrict__ P, int b, int tq_wave, int qcol, int kcol, int vcol, int key0, int nkt, char* smem, f32x16 (&o)[2]) {
;     ...
;   lsum += __shfl_xor(lsum, 32);
;   float inv = 1.f / lsum;
; #pragma unroll
;   for (int i = 0; i < 16; ++i) { o[0][i] = accO[0][i] * inv; o[1][i] = accO[1][i] * inv; }
; DI void store_o(bfr* O, int m, int colbase, int h, const f32x16 (&o)[2]) {
; #pragma unroll
;   for (int dt = 0; dt < 2; ++dt)
; #pragma unroll
;     for (int g4 = 0; g4 < 4; ++g4) {
;       int dv = dt * 32 + 8 * g4 + 4 * h;
;       uint2 pk; pk.x = pack2(o[dt][4 * g4], o[dt][4 * g4 + 1]); pk.y = pack2(o[dt][4 * g4 + 2], o[dt][4 * g4 + 3]);
;       *(uint2*)(O + (size_t)m * DM + colbase + dv) = pk;
;     }
	v_mfma_f32_32x32x16_bf16 v[16:31], v[36:39], v[32:35], v[16:31]
	v_lshl_add_u32 v36, v103, 1, v67
	v_lshl_add_u32 v38, v102, 1, v67
	ds_read_b64 v[36:37], v36 offset:27648
	ds_read_b64 v[38:39], v38 offset:27648
	v_exp_f32_e32 v58, v58
	v_exp_f32_e32 v59, v59
	v_exp_f32_e32 v60, v60
	s_waitcnt lgkmcnt(0)
	v_mfma_f32_32x32x16_bf16 v[0:15], v[36:39], v[32:35], v[0:15]
	v_lshl_add_u32 v36, v100, 1, v80
	v_lshl_add_u32 v38, v101, 1, v80
	v_exp_f32_e32 v61, v61
	v_exp_f32_e32 v62, v62
	v_exp_f32_e32 v63, v63
	v_cvt_pk_bf16_f32 v32, v56, v57
	v_cvt_pk_bf16_f32 v33, v58, v59
	v_cvt_pk_bf16_f32 v34, v60, v61
	v_cvt_pk_bf16_f32 v35, v62, v63
	ds_read_b64 v[36:37], v36 offset:27648
	ds_read_b64 v[38:39], v38 offset:27648
	v_add_f32_e32 v65, v55, v65
	v_add_f32_e32 v65, v40, v65
	v_add_f32_e32 v65, v56, v65
	v_add_f32_e32 v65, v41, v65
	v_add_f32_e32 v65, v57, v65
	v_add_f32_e32 v65, v42, v65
	v_add_f32_e32 v65, v58, v65
	v_add_f32_e32 v65, v43, v65
	v_add_f32_e32 v65, v59, v65
	s_waitcnt lgkmcnt(0)
	v_mfma_f32_32x32x16_bf16 v[16:31], v[36:39], v[32:35], v[16:31]
	v_lshl_add_u32 v36, v99, 1, v67
	v_lshl_add_u32 v38, v98, 1, v67
	v_add_f32_e32 v65, v44, v65
	ds_read_b64 v[36:37], v36 offset:27648
	ds_read_b64 v[38:39], v38 offset:27648
	v_add_f32_e32 v65, v60, v65
	v_add_f32_e32 v65, v45, v65
	v_add_f32_e32 v65, v61, v65
	v_add_f32_e32 v65, v46, v65
	v_add_f32_e32 v65, v62, v65
	v_add_f32_e32 v65, v47, v65
	v_add_f32_e32 v65, v63, v65
	v_fmac_f32_e32 v65, v113, v64
	s_waitcnt lgkmcnt(0)
	v_mfma_f32_32x32x16_bf16 v[0:15], v[36:39], v[32:35], v[0:15]
	ds_bpermute_b32 v32, v91, v65
	s_waitcnt lgkmcnt(0)
	v_add_f32_e32 v32, v65, v32
	v_div_scale_f32 v33, s[8:9], v32, v32, 1.0
	v_rcp_f32_e32 v34, v33
	s_load_dwordx4 s[8:11], s[0:1], 0x100
	s_waitcnt lgkmcnt(0)
	s_mov_b64 s[8:9], 0x2b7c700
	v_fma_f32 v35, -v33, v34, 1.0
	v_fmac_f32_e32 v34, v35, v34
	v_div_scale_f32 v35, vcc, 1.0, v32, 1.0
	v_mul_f32_e32 v36, v35, v34
	v_fma_f32 v37, -v33, v36, v35
	v_fmac_f32_e32 v36, v37, v34
	v_fma_f32 v33, -v33, v36, v35
	v_div_fmas_f32 v33, v33, v34, v36
	v_div_fixup_f32 v32, v33, v32, 1.0
	v_mul_f32_e32 v33, v0, v32
	v_and_or_b32 v0, v89, 31, v97
	v_mul_f32_e32 v34, v1, v32
	v_ashrrev_i32_e32 v1, 31, v0
	v_lshlrev_b64 v[0:1], 11, v[0:1]
	v_mul_f32_e32 v37, v4, v32
	v_lshl_add_u64 v[0:1], s[10:11], 0, v[0:1]
	v_lshrrev_b32_e32 v4, 2, v89
	v_lshl_add_u64 v[0:1], v[0:1], 0, v[152:153]
	v_and_b32_e32 v152, 8, v4
	v_lshl_add_u64 v[0:1], v[0:1], 0, v[152:153]
	v_mul_f32_e32 v38, v5, v32
	v_lshl_add_u64 v[4:5], v[0:1], 0, s[8:9]
	s_mov_b32 s8, 0x2b7c000
	v_add_co_u32_e32 v0, vcc, s8, v0
	v_mul_f32_e32 v16, v16, v32
	s_nop 0
	v_addc_co_u32_e32 v1, vcc, 0, v1, vcc
	v_mul_f32_e32 v17, v17, v32
	v_mul_f32_e32 v18, v18, v32
	v_mul_f32_e32 v35, v2, v32
	v_mul_f32_e32 v19, v19, v32
	v_mul_f32_e32 v36, v3, v32
	v_mul_f32_e32 v20, v20, v32
	v_mul_f32_e32 v21, v21, v32
	v_mul_f32_e32 v22, v22, v32
	v_mul_f32_e32 v23, v23, v32
	v_cvt_pk_bf16_f32 v2, v16, v17
	v_cvt_pk_bf16_f32 v3, v18, v19
	global_store_dwordx2 v[0:1], v[2:3], off offset:1792
	v_cvt_pk_bf16_f32 v0, v20, v21
	v_cvt_pk_bf16_f32 v1, v22, v23
	v_mul_f32_e32 v24, v24, v32
	v_mul_f32_e32 v25, v25, v32
	v_mul_f32_e32 v26, v26, v32
	v_mul_f32_e32 v27, v27, v32
	global_store_dwordx2 v[4:5], v[0:1], off offset:16
	v_cvt_pk_bf16_f32 v0, v24, v25
	v_cvt_pk_bf16_f32 v1, v26, v27
	v_mul_f32_e32 v28, v28, v32
	v_mul_f32_e32 v29, v29, v32
	v_mul_f32_e32 v30, v30, v32
	v_mul_f32_e32 v31, v31, v32
	global_store_dwordx2 v[4:5], v[0:1], off offset:32
	v_cvt_pk_bf16_f32 v0, v28, v29
	v_cvt_pk_bf16_f32 v1, v30, v31
	global_store_dwordx2 v[4:5], v[0:1], off offset:48
	v_cvt_pk_bf16_f32 v0, v33, v34
	v_cvt_pk_bf16_f32 v1, v35, v36
	v_mul_f32_e32 v6, v6, v32
	v_mul_f32_e32 v7, v7, v32
	global_store_dwordx2 v[4:5], v[0:1], off offset:64
	v_cvt_pk_bf16_f32 v0, v37, v38
	v_cvt_pk_bf16_f32 v1, v6, v7
	v_mul_f32_e32 v8, v8, v32
	v_mul_f32_e32 v9, v9, v32
	v_mul_f32_e32 v10, v10, v32
	v_mul_f32_e32 v11, v11, v32
	global_store_dwordx2 v[4:5], v[0:1], off offset:80
	v_cvt_pk_bf16_f32 v0, v8, v9
	v_cvt_pk_bf16_f32 v1, v10, v11
	v_mul_f32_e32 v12, v12, v32
	v_mul_f32_e32 v13, v13, v32
	v_mul_f32_e32 v14, v14, v32
	v_mul_f32_e32 v15, v15, v32
	global_store_dwordx2 v[4:5], v[0:1], off offset:96
	v_cvt_pk_bf16_f32 v0, v12, v13
	v_cvt_pk_bf16_f32 v1, v14, v15
	global_store_dwordx2 v[4:5], v[0:1], off offset:112
